# adds: NSA item prologue staging loads issued together; LayerNorm x/H stores written through (sc1), x still nt
# baseline (speedup 1.0000x reference)
.Lln_loop:
	s_waitcnt vmcnt(16)
	v_lshlrev_b32_e32 v156, 16, v50
	v_and_b32_e32 v157, 0xffff0000, v50
	v_lshlrev_b32_e32 v50, 16, v51
	v_and_b32_e32 v51, 0xffff0000, v51
	v_lshlrev_b32_e32 v158, 16, v52
	v_and_b32_e32 v159, 0xffff0000, v52
	v_lshlrev_b32_e32 v52, 16, v53
	v_and_b32_e32 v53, 0xffff0000, v53
	v_lshlrev_b32_e32 v160, 16, v54
	v_and_b32_e32 v161, 0xffff0000, v54
	v_lshlrev_b32_e32 v54, 16, v55
	v_and_b32_e32 v55, 0xffff0000, v55
	v_lshlrev_b32_e32 v162, 16, v56
	v_and_b32_e32 v163, 0xffff0000, v56
	v_lshlrev_b32_e32 v56, 16, v57
	v_and_b32_e32 v57, 0xffff0000, v57
	v_pk_mul_f32 v[114:115], v[194:195], v[156:157]
	v_pk_mul_f32 v[116:117], v[196:197], v[50:51]
	v_pk_mul_f32 v[118:119], v[198:199], v[158:159]
	v_pk_mul_f32 v[120:121], v[200:201], v[52:53]
	v_pk_mul_f32 v[122:123], v[202:203], v[160:161]
	v_pk_mul_f32 v[124:125], v[204:205], v[54:55]
	v_pk_mul_f32 v[126:127], v[206:207], v[162:163]
	v_pk_mul_f32 v[128:129], v[208:209], v[56:57]
	v_pk_mul_f32 v[114:115], v[10:11], v[114:115]
	v_pk_mul_f32 v[116:117], v[10:11], v[116:117]
	v_pk_mul_f32 v[118:119], v[10:11], v[118:119]
	v_pk_mul_f32 v[120:121], v[10:11], v[120:121]
	v_pk_mul_f32 v[122:123], v[10:11], v[122:123]
	v_pk_mul_f32 v[124:125], v[10:11], v[124:125]
	v_pk_mul_f32 v[126:127], v[10:11], v[126:127]
	v_pk_mul_f32 v[128:129], v[10:11], v[128:129]
	v_pk_fma_f32 v[114:115], v[34:35], s[28:29], v[114:115] op_sel_hi:[1,0,1]
	v_pk_fma_f32 v[116:117], v[36:37], s[28:29], v[116:117] op_sel_hi:[1,0,1]
	v_pk_fma_f32 v[118:119], v[38:39], s[28:29], v[118:119] op_sel_hi:[1,0,1]
	v_pk_fma_f32 v[120:121], v[40:41], s[28:29], v[120:121] op_sel_hi:[1,0,1]
	v_pk_fma_f32 v[122:123], v[42:43], s[28:29], v[122:123] op_sel_hi:[1,0,1]
	v_pk_fma_f32 v[124:125], v[44:45], s[28:29], v[124:125] op_sel_hi:[1,0,1]
	v_pk_fma_f32 v[126:127], v[46:47], s[28:29], v[126:127] op_sel_hi:[1,0,1]
	v_pk_fma_f32 v[128:129], v[48:49], s[28:29], v[128:129] op_sel_hi:[1,0,1]
	v_add_f32_e32 v164, v114, v115
	v_add_f32_e32 v165, v116, v117
	v_add_f32_e32 v166, v118, v119
	v_add_f32_e32 v167, v120, v121
	v_add_f32_e32 v168, v122, v123
	v_add_f32_e32 v169, v124, v125
	v_add_f32_e32 v242, v126, v127
	v_add_f32_e32 v243, v128, v129
	v_add_f32_e32 v164, v164, v165
	v_add_f32_e32 v166, v166, v167
	v_add_f32_e32 v168, v168, v169
	v_add_f32_e32 v242, v242, v243
	v_add_f32_e32 v9, 0, v164
	v_add_f32_e32 v9, v9, v166
	v_add_f32_e32 v9, v9, v168
	v_add_f32_e32 v9, v9, v242
	ds_bpermute_b32 v28, v96, v9
	s_waitcnt lgkmcnt(0)
	v_add_f32_e32 v9, v9, v28
	ds_swizzle_b32 v28, v9 offset:swizzle(SWAP,16)
	s_waitcnt lgkmcnt(0)
	v_add_f32_e32 v9, v9, v28
	ds_swizzle_b32 v28, v9 offset:swizzle(SWAP,8)
	s_waitcnt lgkmcnt(0)
	v_add_f32_e32 v9, v9, v28
	ds_swizzle_b32 v28, v9 offset:swizzle(SWAP,4)
	s_waitcnt lgkmcnt(0)
	v_add_f32_e32 v9, v9, v28
	ds_swizzle_b32 v28, v9 offset:swizzle(SWAP,2)
	s_waitcnt lgkmcnt(0)
	v_add_f32_e32 v9, v9, v28
	ds_swizzle_b32 v28, v9 offset:swizzle(SWAP,1)
	s_waitcnt lgkmcnt(0)
	v_add_f32_e32 v9, v9, v28
	v_fmac_f32_e32 v114, 0xba800000, v9
	v_fmac_f32_e32 v115, 0xba800000, v9
	v_fmac_f32_e32 v116, 0xba800000, v9
	v_fmac_f32_e32 v117, 0xba800000, v9
	v_fmac_f32_e32 v118, 0xba800000, v9
	v_fmac_f32_e32 v119, 0xba800000, v9
	v_fmac_f32_e32 v120, 0xba800000, v9
	v_fmac_f32_e32 v121, 0xba800000, v9
	v_fmac_f32_e32 v122, 0xba800000, v9
	v_fmac_f32_e32 v123, 0xba800000, v9
	v_fmac_f32_e32 v124, 0xba800000, v9
	v_fmac_f32_e32 v125, 0xba800000, v9
	v_fmac_f32_e32 v126, 0xba800000, v9
	v_fmac_f32_e32 v127, 0xba800000, v9
	v_fmac_f32_e32 v128, 0xba800000, v9
	v_fmac_f32_e32 v129, 0xba800000, v9
	v_pk_mul_f32 v[244:245], v[114:115], v[114:115]
	v_pk_mul_f32 v[246:247], v[116:117], v[116:117]
	v_add_f32_e32 v244, v245, v244
	v_add_f32_e32 v246, v246, v247
	v_add_f32_e32 v164, v244, v246
	v_pk_mul_f32 v[244:245], v[118:119], v[118:119]
	v_pk_mul_f32 v[246:247], v[120:121], v[120:121]
	v_add_f32_e32 v244, v245, v244
	v_add_f32_e32 v246, v246, v247
	v_add_f32_e32 v165, v244, v246
	v_mul_f32_e32 v248, v122, v122
	v_mul_f32_e32 v249, v124, v124
	v_fmac_f32_e32 v248, v123, v123
	v_fmac_f32_e32 v249, v125, v125
	v_add_f32_e32 v166, v248, v249
	v_pk_mul_f32 v[244:245], v[126:127], v[126:127]
	v_pk_mul_f32 v[246:247], v[128:129], v[128:129]
	v_add_f32_e32 v244, v244, v245
	v_add_f32_e32 v246, v246, v247
	v_add_f32_e32 v167, v244, v246
	v_add_f32_e32 v164, v164, v165
	v_add_f32_e32 v164, v166, v164
	v_add_f32_e32 v9, v167, v164
	ds_bpermute_b32 v28, v96, v9
	s_waitcnt lgkmcnt(0)
	v_add_f32_e32 v9, v9, v28
	ds_swizzle_b32 v28, v9 offset:swizzle(SWAP,16)
	s_waitcnt lgkmcnt(0)
	v_add_f32_e32 v9, v9, v28
	ds_swizzle_b32 v28, v9 offset:swizzle(SWAP,8)
	s_waitcnt lgkmcnt(0)
	v_add_f32_e32 v9, v9, v28
	ds_swizzle_b32 v28, v9 offset:swizzle(SWAP,4)
	s_waitcnt lgkmcnt(0)
	v_add_f32_e32 v9, v9, v28
	ds_swizzle_b32 v28, v9 offset:swizzle(SWAP,2)
	s_waitcnt lgkmcnt(0)
	v_add_f32_e32 v9, v9, v28
	ds_swizzle_b32 v28, v9 offset:swizzle(SWAP,1)
	s_waitcnt lgkmcnt(0)
	v_add_f32_e32 v9, v9, v28
	v_mov_b32_e32 v28, 0x3727c5ac
	v_fmamk_f32 v9, v9, 0x3a800000, v28
	v_mul_f32_e32 v28, 0x4b800000, v9
	v_cmp_gt_f32_e32 vcc, s37, v9
	s_nop 1
	v_cndmask_b32_e32 v9, v9, v28, vcc
	v_rsq_f32_e32 v9, v9
	s_nop 0
	v_mul_f32_e32 v28, 0x45800000, v9
	v_cndmask_b32_e32 v30, v9, v28, vcc
	v_pk_mul_f32 v[114:115], v[114:115], v[30:31] op_sel_hi:[1,0]
	v_pk_mul_f32 v[116:117], v[116:117], v[30:31] op_sel_hi:[1,0]
	v_pk_fma_f32 v[34:35], v[140:141], v[114:115], v[98:99]
	v_pk_fma_f32 v[36:37], v[142:143], v[116:117], v[100:101]
	global_store_dwordx4 v[86:87], v[34:37], off sc1 nt
	v_pk_fma_f32 v[114:115], v[226:227], v[34:35], v[210:211]
	v_pk_fma_f32 v[116:117], v[228:229], v[36:37], v[212:213]
	s_nop 0
	v_cvt_pk_bf16_f32 v50, v114, v115
	v_cvt_pk_bf16_f32 v51, v116, v117
	global_store_dwordx2 v[88:89], v[50:51], off sc1
	v_pk_mul_f32 v[118:119], v[118:119], v[30:31] op_sel_hi:[1,0]
	v_pk_mul_f32 v[120:121], v[120:121], v[30:31] op_sel_hi:[1,0]
	v_pk_fma_f32 v[38:39], v[144:145], v[118:119], v[102:103]
	v_pk_fma_f32 v[40:41], v[146:147], v[120:121], v[104:105]
	global_store_dwordx4 v[86:87], v[38:41], off offset:1024 sc1 nt
	v_pk_fma_f32 v[118:119], v[230:231], v[38:39], v[214:215]
	v_pk_fma_f32 v[120:121], v[232:233], v[40:41], v[216:217]
	s_nop 0
	v_cvt_pk_bf16_f32 v52, v118, v119
	v_cvt_pk_bf16_f32 v53, v120, v121
	global_store_dwordx2 v[88:89], v[52:53], off offset:512 sc1
	v_pk_mul_f32 v[122:123], v[122:123], v[30:31] op_sel_hi:[1,0]
	v_pk_mul_f32 v[124:125], v[124:125], v[30:31] op_sel_hi:[1,0]
	v_pk_fma_f32 v[42:43], v[148:149], v[122:123], v[106:107]
	v_pk_fma_f32 v[44:45], v[150:151], v[124:125], v[108:109]
	global_store_dwordx4 v[86:87], v[42:45], off offset:2048 sc1 nt
	v_pk_fma_f32 v[122:123], v[234:235], v[42:43], v[218:219]
	v_pk_fma_f32 v[124:125], v[236:237], v[44:45], v[220:221]
	s_nop 0
	v_cvt_pk_bf16_f32 v54, v122, v123
	v_cvt_pk_bf16_f32 v55, v124, v125
	global_store_dwordx2 v[88:89], v[54:55], off offset:1024 sc1
	v_pk_mul_f32 v[126:127], v[126:127], v[30:31] op_sel_hi:[1,0]
	v_pk_mul_f32 v[128:129], v[128:129], v[30:31] op_sel_hi:[1,0]
	v_pk_fma_f32 v[46:47], v[152:153], v[126:127], v[110:111]
	v_pk_fma_f32 v[48:49], v[154:155], v[128:129], v[112:113]
	global_store_dwordx4 v[86:87], v[46:49], off offset:3072 sc1 nt
	v_pk_fma_f32 v[126:127], v[238:239], v[46:47], v[222:223]
	v_pk_fma_f32 v[128:129], v[240:241], v[48:49], v[224:225]
	s_nop 0
	v_cvt_pk_bf16_f32 v56, v126, v127
	v_cvt_pk_bf16_f32 v57, v128, v129
	global_store_dwordx2 v[88:89], v[56:57], off offset:1536 sc1
	v_lshl_add_u64 v[86:87], v[86:87], 0, s[0:1]
	v_lshl_add_u64 v[88:89], v[88:89], 0, s[20:21]
	global_load_dwordx4 v[34:37], v[82:83], off nt
	global_load_dwordx4 v[38:41], v[82:83], off offset:1024 nt
	global_load_dwordx4 v[42:45], v[82:83], off offset:2048 nt
	global_load_dwordx4 v[46:49], v[82:83], off offset:3072 nt
	global_load_dwordx2 v[50:51], v[84:85], off nt
	global_load_dwordx2 v[52:53], v[84:85], off offset:512 nt
	global_load_dwordx2 v[54:55], v[84:85], off offset:1024 nt
	global_load_dwordx2 v[56:57], v[84:85], off offset:1536 nt
	v_lshl_add_u64 v[82:83], v[82:83], 0, s[0:1]
	v_lshl_add_u64 v[84:85], v[84:85], 0, s[20:21]
	s_waitcnt vmcnt(16)
	v_lshlrev_b32_e32 v156, 16, v74
	v_and_b32_e32 v157, 0xffff0000, v74
	v_lshlrev_b32_e32 v74, 16, v75
	v_and_b32_e32 v75, 0xffff0000, v75
	v_lshlrev_b32_e32 v158, 16, v76
	v_and_b32_e32 v159, 0xffff0000, v76
	v_lshlrev_b32_e32 v76, 16, v77
	v_and_b32_e32 v77, 0xffff0000, v77
	v_lshlrev_b32_e32 v160, 16, v78
	v_and_b32_e32 v161, 0xffff0000, v78
	v_lshlrev_b32_e32 v78, 16, v79
	v_and_b32_e32 v79, 0xffff0000, v79
	v_lshlrev_b32_e32 v162, 16, v80
	v_and_b32_e32 v163, 0xffff0000, v80
	v_lshlrev_b32_e32 v80, 16, v81
	v_and_b32_e32 v81, 0xffff0000, v81
	v_pk_mul_f32 v[114:115], v[194:195], v[156:157]
	v_pk_mul_f32 v[116:117], v[196:197], v[74:75]
	v_pk_mul_f32 v[118:119], v[198:199], v[158:159]
	v_pk_mul_f32 v[120:121], v[200:201], v[76:77]
	v_pk_mul_f32 v[122:123], v[202:203], v[160:161]
	v_pk_mul_f32 v[124:125], v[204:205], v[78:79]
	v_pk_mul_f32 v[126:127], v[206:207], v[162:163]
	v_pk_mul_f32 v[128:129], v[208:209], v[80:81]
	v_pk_mul_f32 v[114:115], v[10:11], v[114:115]
	v_pk_mul_f32 v[116:117], v[10:11], v[116:117]
	v_pk_mul_f32 v[118:119], v[10:11], v[118:119]
	v_pk_mul_f32 v[120:121], v[10:11], v[120:121]
	v_pk_mul_f32 v[122:123], v[10:11], v[122:123]
	v_pk_mul_f32 v[124:125], v[10:11], v[124:125]
	v_pk_mul_f32 v[126:127], v[10:11], v[126:127]
	v_pk_mul_f32 v[128:129], v[10:11], v[128:129]
	v_pk_fma_f32 v[114:115], v[58:59], s[28:29], v[114:115] op_sel_hi:[1,0,1]
	v_pk_fma_f32 v[116:117], v[60:61], s[28:29], v[116:117] op_sel_hi:[1,0,1]
	v_pk_fma_f32 v[118:119], v[62:63], s[28:29], v[118:119] op_sel_hi:[1,0,1]
	v_pk_fma_f32 v[120:121], v[64:65], s[28:29], v[120:121] op_sel_hi:[1,0,1]
	v_pk_fma_f32 v[122:123], v[66:67], s[28:29], v[122:123] op_sel_hi:[1,0,1]
	v_pk_fma_f32 v[124:125], v[68:69], s[28:29], v[124:125] op_sel_hi:[1,0,1]
	v_pk_fma_f32 v[126:127], v[70:71], s[28:29], v[126:127] op_sel_hi:[1,0,1]
	v_pk_fma_f32 v[128:129], v[72:73], s[28:29], v[128:129] op_sel_hi:[1,0,1]
	v_add_f32_e32 v164, v114, v115
	v_add_f32_e32 v165, v116, v117
	v_add_f32_e32 v166, v118, v119
	v_add_f32_e32 v167, v120, v121
	v_add_f32_e32 v168, v122, v123
	v_add_f32_e32 v169, v124, v125
	v_add_f32_e32 v242, v126, v127
	v_add_f32_e32 v243, v128, v129
	v_add_f32_e32 v164, v164, v165
	v_add_f32_e32 v166, v166, v167
	v_add_f32_e32 v168, v168, v169
	v_add_f32_e32 v242, v242, v243
	v_add_f32_e32 v9, 0, v164
	v_add_f32_e32 v9, v9, v166
	v_add_f32_e32 v9, v9, v168
	v_add_f32_e32 v9, v9, v242
	ds_bpermute_b32 v28, v96, v9
	s_waitcnt lgkmcnt(0)
	v_add_f32_e32 v9, v9, v28
	ds_swizzle_b32 v28, v9 offset:swizzle(SWAP,16)
	s_waitcnt lgkmcnt(0)
	v_add_f32_e32 v9, v9, v28
	ds_swizzle_b32 v28, v9 offset:swizzle(SWAP,8)
	s_waitcnt lgkmcnt(0)
	v_add_f32_e32 v9, v9, v28
	ds_swizzle_b32 v28, v9 offset:swizzle(SWAP,4)
	s_waitcnt lgkmcnt(0)
	v_add_f32_e32 v9, v9, v28
	ds_swizzle_b32 v28, v9 offset:swizzle(SWAP,2)
	s_waitcnt lgkmcnt(0)
	v_add_f32_e32 v9, v9, v28
	ds_swizzle_b32 v28, v9 offset:swizzle(SWAP,1)
	s_waitcnt lgkmcnt(0)
	v_add_f32_e32 v9, v9, v28
	v_fmac_f32_e32 v114, 0xba800000, v9
	v_fmac_f32_e32 v115, 0xba800000, v9
	v_fmac_f32_e32 v116, 0xba800000, v9
	v_fmac_f32_e32 v117, 0xba800000, v9
	v_fmac_f32_e32 v118, 0xba800000, v9
	v_fmac_f32_e32 v119, 0xba800000, v9
	v_fmac_f32_e32 v120, 0xba800000, v9
	v_fmac_f32_e32 v121, 0xba800000, v9
	v_fmac_f32_e32 v122, 0xba800000, v9
	v_fmac_f32_e32 v123, 0xba800000, v9
	v_fmac_f32_e32 v124, 0xba800000, v9
	v_fmac_f32_e32 v125, 0xba800000, v9
	v_fmac_f32_e32 v126, 0xba800000, v9
	v_fmac_f32_e32 v127, 0xba800000, v9
	v_fmac_f32_e32 v128, 0xba800000, v9
	v_fmac_f32_e32 v129, 0xba800000, v9
	v_pk_mul_f32 v[244:245], v[114:115], v[114:115]
	v_pk_mul_f32 v[246:247], v[116:117], v[116:117]
	v_add_f32_e32 v244, v245, v244
	v_add_f32_e32 v246, v246, v247
	v_add_f32_e32 v164, v244, v246
	v_pk_mul_f32 v[244:245], v[118:119], v[118:119]
	v_pk_mul_f32 v[246:247], v[120:121], v[120:121]
	v_add_f32_e32 v244, v245, v244
	v_add_f32_e32 v246, v246, v247
	v_add_f32_e32 v165, v244, v246
	v_mul_f32_e32 v248, v122, v122
	v_mul_f32_e32 v249, v124, v124
	v_fmac_f32_e32 v248, v123, v123
	v_fmac_f32_e32 v249, v125, v125
	v_add_f32_e32 v166, v248, v249
	v_pk_mul_f32 v[244:245], v[126:127], v[126:127]
	v_pk_mul_f32 v[246:247], v[128:129], v[128:129]
	v_add_f32_e32 v244, v244, v245
	v_add_f32_e32 v246, v246, v247
	v_add_f32_e32 v167, v244, v246
	v_add_f32_e32 v164, v164, v165
	v_add_f32_e32 v164, v166, v164
	v_add_f32_e32 v9, v167, v164
	ds_bpermute_b32 v28, v96, v9
	s_waitcnt lgkmcnt(0)
	v_add_f32_e32 v9, v9, v28
	ds_swizzle_b32 v28, v9 offset:swizzle(SWAP,16)
	s_waitcnt lgkmcnt(0)
	v_add_f32_e32 v9, v9, v28
	ds_swizzle_b32 v28, v9 offset:swizzle(SWAP,8)
	s_waitcnt lgkmcnt(0)
	v_add_f32_e32 v9, v9, v28
	ds_swizzle_b32 v28, v9 offset:swizzle(SWAP,4)
	s_waitcnt lgkmcnt(0)
	v_add_f32_e32 v9, v9, v28
	ds_swizzle_b32 v28, v9 offset:swizzle(SWAP,2)
	s_waitcnt lgkmcnt(0)
	v_add_f32_e32 v9, v9, v28
	ds_swizzle_b32 v28, v9 offset:swizzle(SWAP,1)
	s_waitcnt lgkmcnt(0)
	v_add_f32_e32 v9, v9, v28
	v_mov_b32_e32 v28, 0x3727c5ac
	v_fmamk_f32 v9, v9, 0x3a800000, v28
	v_mul_f32_e32 v28, 0x4b800000, v9
	v_cmp_gt_f32_e32 vcc, s37, v9
	s_nop 1
	v_cndmask_b32_e32 v9, v9, v28, vcc
	v_rsq_f32_e32 v9, v9
	s_nop 0
	v_mul_f32_e32 v28, 0x45800000, v9
	v_cndmask_b32_e32 v30, v9, v28, vcc
	v_pk_mul_f32 v[114:115], v[114:115], v[30:31] op_sel_hi:[1,0]
	v_pk_mul_f32 v[116:117], v[116:117], v[30:31] op_sel_hi:[1,0]
	v_pk_fma_f32 v[58:59], v[140:141], v[114:115], v[98:99]
	v_pk_fma_f32 v[60:61], v[142:143], v[116:117], v[100:101]
	global_store_dwordx4 v[86:87], v[58:61], off sc1 nt
	v_pk_fma_f32 v[114:115], v[226:227], v[58:59], v[210:211]
	v_pk_fma_f32 v[116:117], v[228:229], v[60:61], v[212:213]
	s_nop 0
	v_cvt_pk_bf16_f32 v74, v114, v115
	v_cvt_pk_bf16_f32 v75, v116, v117
	global_store_dwordx2 v[88:89], v[74:75], off sc1
	v_pk_mul_f32 v[118:119], v[118:119], v[30:31] op_sel_hi:[1,0]
	v_pk_mul_f32 v[120:121], v[120:121], v[30:31] op_sel_hi:[1,0]
	v_pk_fma_f32 v[62:63], v[144:145], v[118:119], v[102:103]
	v_pk_fma_f32 v[64:65], v[146:147], v[120:121], v[104:105]
	global_store_dwordx4 v[86:87], v[62:65], off offset:1024 sc1 nt
	v_pk_fma_f32 v[118:119], v[230:231], v[62:63], v[214:215]
	v_pk_fma_f32 v[120:121], v[232:233], v[64:65], v[216:217]
	s_nop 0
	v_cvt_pk_bf16_f32 v76, v118, v119
	v_cvt_pk_bf16_f32 v77, v120, v121
	global_store_dwordx2 v[88:89], v[76:77], off offset:512 sc1
	v_pk_mul_f32 v[122:123], v[122:123], v[30:31] op_sel_hi:[1,0]
	v_pk_mul_f32 v[124:125], v[124:125], v[30:31] op_sel_hi:[1,0]
	v_pk_fma_f32 v[66:67], v[148:149], v[122:123], v[106:107]
	v_pk_fma_f32 v[68:69], v[150:151], v[124:125], v[108:109]
	global_store_dwordx4 v[86:87], v[66:69], off offset:2048 sc1 nt
	v_pk_fma_f32 v[122:123], v[234:235], v[66:67], v[218:219]
	v_pk_fma_f32 v[124:125], v[236:237], v[68:69], v[220:221]
	s_nop 0
	v_cvt_pk_bf16_f32 v78, v122, v123
	v_cvt_pk_bf16_f32 v79, v124, v125
	global_store_dwordx2 v[88:89], v[78:79], off offset:1024 sc1
	v_pk_mul_f32 v[126:127], v[126:127], v[30:31] op_sel_hi:[1,0]
	v_pk_mul_f32 v[128:129], v[128:129], v[30:31] op_sel_hi:[1,0]
	v_pk_fma_f32 v[70:71], v[152:153], v[126:127], v[110:111]
	v_pk_fma_f32 v[72:73], v[154:155], v[128:129], v[112:113]
	global_store_dwordx4 v[86:87], v[70:73], off offset:3072 sc1 nt
	v_pk_fma_f32 v[126:127], v[238:239], v[70:71], v[222:223]
	v_pk_fma_f32 v[128:129], v[240:241], v[72:73], v[224:225]
	s_nop 0
	v_cvt_pk_bf16_f32 v80, v126, v127
	v_cvt_pk_bf16_f32 v81, v128, v129
	global_store_dwordx2 v[88:89], v[80:81], off offset:1536 sc1
	v_lshl_add_u64 v[86:87], v[86:87], 0, s[0:1]
	v_lshl_add_u64 v[88:89], v[88:89], 0, s[20:21]
	global_load_dwordx4 v[58:61], v[82:83], off nt
	global_load_dwordx4 v[62:65], v[82:83], off offset:1024 nt
	global_load_dwordx4 v[66:69], v[82:83], off offset:2048 nt
	global_load_dwordx4 v[70:73], v[82:83], off offset:3072 nt
	global_load_dwordx2 v[74:75], v[84:85], off nt
	global_load_dwordx2 v[76:77], v[84:85], off offset:512 nt
	global_load_dwordx2 v[78:79], v[84:85], off offset:1024 nt
	global_load_dwordx2 v[80:81], v[84:85], off offset:1536 nt
	v_lshl_add_u64 v[82:83], v[82:83], 0, s[0:1]
	v_lshl_add_u64 v[84:85], v[84:85], 0, s[20:21]
	s_add_i32 s6, s6, -1
	s_cmp_lg_u32 s6, 0
	s_cbranch_scc1 .Lln_loop
	s_waitcnt vmcnt(16)
	v_lshlrev_b32_e32 v156, 16, v50
	v_and_b32_e32 v157, 0xffff0000, v50
	v_lshlrev_b32_e32 v50, 16, v51
	v_and_b32_e32 v51, 0xffff0000, v51
	v_lshlrev_b32_e32 v158, 16, v52
	v_and_b32_e32 v159, 0xffff0000, v52
	v_lshlrev_b32_e32 v52, 16, v53
	v_and_b32_e32 v53, 0xffff0000, v53
	v_lshlrev_b32_e32 v160, 16, v54
	v_and_b32_e32 v161, 0xffff0000, v54
	v_lshlrev_b32_e32 v54, 16, v55
	v_and_b32_e32 v55, 0xffff0000, v55
	v_lshlrev_b32_e32 v162, 16, v56
	v_and_b32_e32 v163, 0xffff0000, v56
	v_lshlrev_b32_e32 v56, 16, v57
	v_and_b32_e32 v57, 0xffff0000, v57
	v_pk_mul_f32 v[114:115], v[194:195], v[156:157]
	v_pk_mul_f32 v[116:117], v[196:197], v[50:51]
	v_pk_mul_f32 v[118:119], v[198:199], v[158:159]
	v_pk_mul_f32 v[120:121], v[200:201], v[52:53]
	v_pk_mul_f32 v[122:123], v[202:203], v[160:161]
	v_pk_mul_f32 v[124:125], v[204:205], v[54:55]
	v_pk_mul_f32 v[126:127], v[206:207], v[162:163]
	v_pk_mul_f32 v[128:129], v[208:209], v[56:57]
	v_pk_mul_f32 v[114:115], v[10:11], v[114:115]
	v_pk_mul_f32 v[116:117], v[10:11], v[116:117]
	v_pk_mul_f32 v[118:119], v[10:11], v[118:119]
	v_pk_mul_f32 v[120:121], v[10:11], v[120:121]
	v_pk_mul_f32 v[122:123], v[10:11], v[122:123]
	v_pk_mul_f32 v[124:125], v[10:11], v[124:125]
	v_pk_mul_f32 v[126:127], v[10:11], v[126:127]
	v_pk_mul_f32 v[128:129], v[10:11], v[128:129]
	v_pk_fma_f32 v[114:115], v[34:35], s[28:29], v[114:115] op_sel_hi:[1,0,1]
	v_pk_fma_f32 v[116:117], v[36:37], s[28:29], v[116:117] op_sel_hi:[1,0,1]
	v_pk_fma_f32 v[118:119], v[38:39], s[28:29], v[118:119] op_sel_hi:[1,0,1]
	v_pk_fma_f32 v[120:121], v[40:41], s[28:29], v[120:121] op_sel_hi:[1,0,1]
	v_pk_fma_f32 v[122:123], v[42:43], s[28:29], v[122:123] op_sel_hi:[1,0,1]
	v_pk_fma_f32 v[124:125], v[44:45], s[28:29], v[124:125] op_sel_hi:[1,0,1]
	v_pk_fma_f32 v[126:127], v[46:47], s[28:29], v[126:127] op_sel_hi:[1,0,1]
	v_pk_fma_f32 v[128:129], v[48:49], s[28:29], v[128:129] op_sel_hi:[1,0,1]
	v_add_f32_e32 v164, v114, v115
	v_add_f32_e32 v165, v116, v117
	v_add_f32_e32 v166, v118, v119
	v_add_f32_e32 v167, v120, v121
	v_add_f32_e32 v168, v122, v123
	v_add_f32_e32 v169, v124, v125
	v_add_f32_e32 v242, v126, v127
	v_add_f32_e32 v243, v128, v129
	v_add_f32_e32 v164, v164, v165
	v_add_f32_e32 v166, v166, v167
	v_add_f32_e32 v168, v168, v169
	v_add_f32_e32 v242, v242, v243
	v_add_f32_e32 v9, 0, v164
	v_add_f32_e32 v9, v9, v166
	v_add_f32_e32 v9, v9, v168
	v_add_f32_e32 v9, v9, v242
	ds_bpermute_b32 v28, v96, v9
	s_waitcnt lgkmcnt(0)
	v_add_f32_e32 v9, v9, v28
	ds_swizzle_b32 v28, v9 offset:swizzle(SWAP,16)
	s_waitcnt lgkmcnt(0)
	v_add_f32_e32 v9, v9, v28
	ds_swizzle_b32 v28, v9 offset:swizzle(SWAP,8)
	s_waitcnt lgkmcnt(0)
	v_add_f32_e32 v9, v9, v28
	ds_swizzle_b32 v28, v9 offset:swizzle(SWAP,4)
	s_waitcnt lgkmcnt(0)
	v_add_f32_e32 v9, v9, v28
	ds_swizzle_b32 v28, v9 offset:swizzle(SWAP,2)
	s_waitcnt lgkmcnt(0)
	v_add_f32_e32 v9, v9, v28
	ds_swizzle_b32 v28, v9 offset:swizzle(SWAP,1)
	s_waitcnt lgkmcnt(0)
	v_add_f32_e32 v9, v9, v28
	v_fmac_f32_e32 v114, 0xba800000, v9
	v_fmac_f32_e32 v115, 0xba800000, v9
	v_fmac_f32_e32 v116, 0xba800000, v9
	v_fmac_f32_e32 v117, 0xba800000, v9
	v_fmac_f32_e32 v118, 0xba800000, v9
	v_fmac_f32_e32 v119, 0xba800000, v9
	v_fmac_f32_e32 v120, 0xba800000, v9
	v_fmac_f32_e32 v121, 0xba800000, v9
	v_fmac_f32_e32 v122, 0xba800000, v9
	v_fmac_f32_e32 v123, 0xba800000, v9
	v_fmac_f32_e32 v124, 0xba800000, v9
	v_fmac_f32_e32 v125, 0xba800000, v9
	v_fmac_f32_e32 v126, 0xba800000, v9
	v_fmac_f32_e32 v127, 0xba800000, v9
	v_fmac_f32_e32 v128, 0xba800000, v9
	v_fmac_f32_e32 v129, 0xba800000, v9
	v_pk_mul_f32 v[244:245], v[114:115], v[114:115]
	v_pk_mul_f32 v[246:247], v[116:117], v[116:117]
	v_add_f32_e32 v244, v245, v244
	v_add_f32_e32 v246, v246, v247
	v_add_f32_e32 v164, v244, v246
	v_pk_mul_f32 v[244:245], v[118:119], v[118:119]
	v_pk_mul_f32 v[246:247], v[120:121], v[120:121]
	v_add_f32_e32 v244, v245, v244
	v_add_f32_e32 v246, v246, v247
	v_add_f32_e32 v165, v244, v246
	v_mul_f32_e32 v248, v122, v122
	v_mul_f32_e32 v249, v124, v124
	v_fmac_f32_e32 v248, v123, v123
	v_fmac_f32_e32 v249, v125, v125
	v_add_f32_e32 v166, v248, v249
	v_pk_mul_f32 v[244:245], v[126:127], v[126:127]
	v_pk_mul_f32 v[246:247], v[128:129], v[128:129]
	v_add_f32_e32 v244, v244, v245
	v_add_f32_e32 v246, v246, v247
	v_add_f32_e32 v167, v244, v246
	v_add_f32_e32 v164, v164, v165
	v_add_f32_e32 v164, v166, v164
	v_add_f32_e32 v9, v167, v164
	ds_bpermute_b32 v28, v96, v9
	s_waitcnt lgkmcnt(0)
	v_add_f32_e32 v9, v9, v28
	ds_swizzle_b32 v28, v9 offset:swizzle(SWAP,16)
	s_waitcnt lgkmcnt(0)
	v_add_f32_e32 v9, v9, v28
	ds_swizzle_b32 v28, v9 offset:swizzle(SWAP,8)
	s_waitcnt lgkmcnt(0)
	v_add_f32_e32 v9, v9, v28
	ds_swizzle_b32 v28, v9 offset:swizzle(SWAP,4)
	s_waitcnt lgkmcnt(0)
	v_add_f32_e32 v9, v9, v28
	ds_swizzle_b32 v28, v9 offset:swizzle(SWAP,2)
	s_waitcnt lgkmcnt(0)
	v_add_f32_e32 v9, v9, v28
	ds_swizzle_b32 v28, v9 offset:swizzle(SWAP,1)
	s_waitcnt lgkmcnt(0)
	v_add_f32_e32 v9, v9, v28
	v_mov_b32_e32 v28, 0x3727c5ac
	v_fmamk_f32 v9, v9, 0x3a800000, v28
	v_mul_f32_e32 v28, 0x4b800000, v9
	v_cmp_gt_f32_e32 vcc, s37, v9
	s_nop 1
	v_cndmask_b32_e32 v9, v9, v28, vcc
	v_rsq_f32_e32 v9, v9
	s_nop 0
	v_mul_f32_e32 v28, 0x45800000, v9
	v_cndmask_b32_e32 v30, v9, v28, vcc
	v_pk_mul_f32 v[114:115], v[114:115], v[30:31] op_sel_hi:[1,0]
	v_pk_mul_f32 v[116:117], v[116:117], v[30:31] op_sel_hi:[1,0]
	v_pk_fma_f32 v[34:35], v[140:141], v[114:115], v[98:99]
	v_pk_fma_f32 v[36:37], v[142:143], v[116:117], v[100:101]
	global_store_dwordx4 v[86:87], v[34:37], off sc1 nt
	v_pk_fma_f32 v[114:115], v[226:227], v[34:35], v[210:211]
	v_pk_fma_f32 v[116:117], v[228:229], v[36:37], v[212:213]
	s_nop 0
	v_cvt_pk_bf16_f32 v50, v114, v115
	v_cvt_pk_bf16_f32 v51, v116, v117
	global_store_dwordx2 v[88:89], v[50:51], off sc1
	v_pk_mul_f32 v[118:119], v[118:119], v[30:31] op_sel_hi:[1,0]
	v_pk_mul_f32 v[120:121], v[120:121], v[30:31] op_sel_hi:[1,0]
	v_pk_fma_f32 v[38:39], v[144:145], v[118:119], v[102:103]
	v_pk_fma_f32 v[40:41], v[146:147], v[120:121], v[104:105]
	global_store_dwordx4 v[86:87], v[38:41], off offset:1024 sc1 nt
	v_pk_fma_f32 v[118:119], v[230:231], v[38:39], v[214:215]
	v_pk_fma_f32 v[120:121], v[232:233], v[40:41], v[216:217]
	s_nop 0
	v_cvt_pk_bf16_f32 v52, v118, v119
	v_cvt_pk_bf16_f32 v53, v120, v121
	global_store_dwordx2 v[88:89], v[52:53], off offset:512 sc1
	v_pk_mul_f32 v[122:123], v[122:123], v[30:31] op_sel_hi:[1,0]
	v_pk_mul_f32 v[124:125], v[124:125], v[30:31] op_sel_hi:[1,0]
	v_pk_fma_f32 v[42:43], v[148:149], v[122:123], v[106:107]
	v_pk_fma_f32 v[44:45], v[150:151], v[124:125], v[108:109]
	global_store_dwordx4 v[86:87], v[42:45], off offset:2048 sc1 nt
	v_pk_fma_f32 v[122:123], v[234:235], v[42:43], v[218:219]
	v_pk_fma_f32 v[124:125], v[236:237], v[44:45], v[220:221]
	s_nop 0
	v_cvt_pk_bf16_f32 v54, v122, v123
	v_cvt_pk_bf16_f32 v55, v124, v125
	global_store_dwordx2 v[88:89], v[54:55], off offset:1024 sc1
	v_pk_mul_f32 v[126:127], v[126:127], v[30:31] op_sel_hi:[1,0]
	v_pk_mul_f32 v[128:129], v[128:129], v[30:31] op_sel_hi:[1,0]
	v_pk_fma_f32 v[46:47], v[152:153], v[126:127], v[110:111]
	v_pk_fma_f32 v[48:49], v[154:155], v[128:129], v[112:113]
	global_store_dwordx4 v[86:87], v[46:49], off offset:3072 sc1 nt
	v_pk_fma_f32 v[126:127], v[238:239], v[46:47], v[222:223]
	v_pk_fma_f32 v[128:129], v[240:241], v[48:49], v[224:225]
	s_nop 0
	v_cvt_pk_bf16_f32 v56, v126, v127
	v_cvt_pk_bf16_f32 v57, v128, v129
	global_store_dwordx2 v[88:89], v[56:57], off offset:1536 sc1
	v_lshl_add_u64 v[86:87], v[86:87], 0, s[0:1]
	v_lshl_add_u64 v[88:89], v[88:89], 0, s[20:21]
	s_waitcnt vmcnt(8)
	v_lshlrev_b32_e32 v156, 16, v74
	v_and_b32_e32 v157, 0xffff0000, v74
	v_lshlrev_b32_e32 v74, 16, v75
	v_and_b32_e32 v75, 0xffff0000, v75
	v_lshlrev_b32_e32 v158, 16, v76
	v_and_b32_e32 v159, 0xffff0000, v76
	v_lshlrev_b32_e32 v76, 16, v77
	v_and_b32_e32 v77, 0xffff0000, v77
	v_lshlrev_b32_e32 v160, 16, v78
	v_and_b32_e32 v161, 0xffff0000, v78
	v_lshlrev_b32_e32 v78, 16, v79
	v_and_b32_e32 v79, 0xffff0000, v79
	v_lshlrev_b32_e32 v162, 16, v80
	v_and_b32_e32 v163, 0xffff0000, v80
	v_lshlrev_b32_e32 v80, 16, v81
	v_and_b32_e32 v81, 0xffff0000, v81
	v_pk_mul_f32 v[114:115], v[194:195], v[156:157]
	v_pk_mul_f32 v[116:117], v[196:197], v[74:75]
	v_pk_mul_f32 v[118:119], v[198:199], v[158:159]
	v_pk_mul_f32 v[120:121], v[200:201], v[76:77]
	v_pk_mul_f32 v[122:123], v[202:203], v[160:161]
	v_pk_mul_f32 v[124:125], v[204:205], v[78:79]
	v_pk_mul_f32 v[126:127], v[206:207], v[162:163]
	v_pk_mul_f32 v[128:129], v[208:209], v[80:81]
	v_pk_mul_f32 v[114:115], v[10:11], v[114:115]
	v_pk_mul_f32 v[116:117], v[10:11], v[116:117]
	v_pk_mul_f32 v[118:119], v[10:11], v[118:119]
	v_pk_mul_f32 v[120:121], v[10:11], v[120:121]
	v_pk_mul_f32 v[122:123], v[10:11], v[122:123]
	v_pk_mul_f32 v[124:125], v[10:11], v[124:125]
	v_pk_mul_f32 v[126:127], v[10:11], v[126:127]
	v_pk_mul_f32 v[128:129], v[10:11], v[128:129]
	v_pk_fma_f32 v[114:115], v[58:59], s[28:29], v[114:115] op_sel_hi:[1,0,1]
	v_pk_fma_f32 v[116:117], v[60:61], s[28:29], v[116:117] op_sel_hi:[1,0,1]
	v_pk_fma_f32 v[118:119], v[62:63], s[28:29], v[118:119] op_sel_hi:[1,0,1]
	v_pk_fma_f32 v[120:121], v[64:65], s[28:29], v[120:121] op_sel_hi:[1,0,1]
	v_pk_fma_f32 v[122:123], v[66:67], s[28:29], v[122:123] op_sel_hi:[1,0,1]
	v_pk_fma_f32 v[124:125], v[68:69], s[28:29], v[124:125] op_sel_hi:[1,0,1]
	v_pk_fma_f32 v[126:127], v[70:71], s[28:29], v[126:127] op_sel_hi:[1,0,1]
	v_pk_fma_f32 v[128:129], v[72:73], s[28:29], v[128:129] op_sel_hi:[1,0,1]
	v_add_f32_e32 v164, v114, v115
	v_add_f32_e32 v165, v116, v117
	v_add_f32_e32 v166, v118, v119
	v_add_f32_e32 v167, v120, v121
	v_add_f32_e32 v168, v122, v123
	v_add_f32_e32 v169, v124, v125
	v_add_f32_e32 v242, v126, v127
	v_add_f32_e32 v243, v128, v129
	v_add_f32_e32 v164, v164, v165
	v_add_f32_e32 v166, v166, v167
	v_add_f32_e32 v168, v168, v169
	v_add_f32_e32 v242, v242, v243
	v_add_f32_e32 v9, 0, v164
	v_add_f32_e32 v9, v9, v166
	v_add_f32_e32 v9, v9, v168
	v_add_f32_e32 v9, v9, v242
	ds_bpermute_b32 v28, v96, v9
	s_waitcnt lgkmcnt(0)
	v_add_f32_e32 v9, v9, v28
	ds_swizzle_b32 v28, v9 offset:swizzle(SWAP,16)
	s_waitcnt lgkmcnt(0)
	v_add_f32_e32 v9, v9, v28
	ds_swizzle_b32 v28, v9 offset:swizzle(SWAP,8)
	s_waitcnt lgkmcnt(0)
	v_add_f32_e32 v9, v9, v28
	ds_swizzle_b32 v28, v9 offset:swizzle(SWAP,4)
	s_waitcnt lgkmcnt(0)
	v_add_f32_e32 v9, v9, v28
	ds_swizzle_b32 v28, v9 offset:swizzle(SWAP,2)
	s_waitcnt lgkmcnt(0)
	v_add_f32_e32 v9, v9, v28
	ds_swizzle_b32 v28, v9 offset:swizzle(SWAP,1)
	s_waitcnt lgkmcnt(0)
	v_add_f32_e32 v9, v9, v28
	v_fmac_f32_e32 v114, 0xba800000, v9
	v_fmac_f32_e32 v115, 0xba800000, v9
	v_fmac_f32_e32 v116, 0xba800000, v9
	v_fmac_f32_e32 v117, 0xba800000, v9
	v_fmac_f32_e32 v118, 0xba800000, v9
	v_fmac_f32_e32 v119, 0xba800000, v9
	v_fmac_f32_e32 v120, 0xba800000, v9
	v_fmac_f32_e32 v121, 0xba800000, v9
	v_fmac_f32_e32 v122, 0xba800000, v9
	v_fmac_f32_e32 v123, 0xba800000, v9
	v_fmac_f32_e32 v124, 0xba800000, v9
	v_fmac_f32_e32 v125, 0xba800000, v9
	v_fmac_f32_e32 v126, 0xba800000, v9
	v_fmac_f32_e32 v127, 0xba800000, v9
	v_fmac_f32_e32 v128, 0xba800000, v9
	v_fmac_f32_e32 v129, 0xba800000, v9
	v_pk_mul_f32 v[244:245], v[114:115], v[114:115]
	v_pk_mul_f32 v[246:247], v[116:117], v[116:117]
	v_add_f32_e32 v244, v245, v244
	v_add_f32_e32 v246, v246, v247
	v_add_f32_e32 v164, v244, v246
	v_pk_mul_f32 v[244:245], v[118:119], v[118:119]
	v_pk_mul_f32 v[246:247], v[120:121], v[120:121]
	v_add_f32_e32 v244, v245, v244
	v_add_f32_e32 v246, v246, v247
	v_add_f32_e32 v165, v244, v246
	v_mul_f32_e32 v248, v122, v122
	v_mul_f32_e32 v249, v124, v124
	v_fmac_f32_e32 v248, v123, v123
	v_fmac_f32_e32 v249, v125, v125
	v_add_f32_e32 v166, v248, v249
	v_pk_mul_f32 v[244:245], v[126:127], v[126:127]
	v_pk_mul_f32 v[246:247], v[128:129], v[128:129]
	v_add_f32_e32 v244, v244, v245
	v_add_f32_e32 v246, v246, v247
	v_add_f32_e32 v167, v244, v246
	v_add_f32_e32 v164, v164, v165
	v_add_f32_e32 v164, v166, v164
	v_add_f32_e32 v9, v167, v164
	ds_bpermute_b32 v28, v96, v9
	s_waitcnt lgkmcnt(0)
	v_add_f32_e32 v9, v9, v28
	ds_swizzle_b32 v28, v9 offset:swizzle(SWAP,16)
	s_waitcnt lgkmcnt(0)
	v_add_f32_e32 v9, v9, v28
	ds_swizzle_b32 v28, v9 offset:swizzle(SWAP,8)
	s_waitcnt lgkmcnt(0)
	v_add_f32_e32 v9, v9, v28
	ds_swizzle_b32 v28, v9 offset:swizzle(SWAP,4)
	s_waitcnt lgkmcnt(0)
	v_add_f32_e32 v9, v9, v28
	ds_swizzle_b32 v28, v9 offset:swizzle(SWAP,2)
	s_waitcnt lgkmcnt(0)
	v_add_f32_e32 v9, v9, v28
	ds_swizzle_b32 v28, v9 offset:swizzle(SWAP,1)
	s_waitcnt lgkmcnt(0)
	v_add_f32_e32 v9, v9, v28
	v_mov_b32_e32 v28, 0x3727c5ac
	v_fmamk_f32 v9, v9, 0x3a800000, v28
	v_mul_f32_e32 v28, 0x4b800000, v9
	v_cmp_gt_f32_e32 vcc, s37, v9
	s_nop 1
	v_cndmask_b32_e32 v9, v9, v28, vcc
	v_rsq_f32_e32 v9, v9
	s_nop 0
	v_mul_f32_e32 v28, 0x45800000, v9
	v_cndmask_b32_e32 v30, v9, v28, vcc
	v_pk_mul_f32 v[114:115], v[114:115], v[30:31] op_sel_hi:[1,0]
	v_pk_mul_f32 v[116:117], v[116:117], v[30:31] op_sel_hi:[1,0]
	v_pk_fma_f32 v[58:59], v[140:141], v[114:115], v[98:99]
	v_pk_fma_f32 v[60:61], v[142:143], v[116:117], v[100:101]
	global_store_dwordx4 v[86:87], v[58:61], off sc1 nt
	v_pk_fma_f32 v[114:115], v[226:227], v[58:59], v[210:211]
	v_pk_fma_f32 v[116:117], v[228:229], v[60:61], v[212:213]
	s_nop 0
	v_cvt_pk_bf16_f32 v74, v114, v115
	v_cvt_pk_bf16_f32 v75, v116, v117
	global_store_dwordx2 v[88:89], v[74:75], off sc1
	v_pk_mul_f32 v[118:119], v[118:119], v[30:31] op_sel_hi:[1,0]
	v_pk_mul_f32 v[120:121], v[120:121], v[30:31] op_sel_hi:[1,0]
	v_pk_fma_f32 v[62:63], v[144:145], v[118:119], v[102:103]
	v_pk_fma_f32 v[64:65], v[146:147], v[120:121], v[104:105]
	global_store_dwordx4 v[86:87], v[62:65], off offset:1024 sc1 nt
	v_pk_fma_f32 v[118:119], v[230:231], v[62:63], v[214:215]
	v_pk_fma_f32 v[120:121], v[232:233], v[64:65], v[216:217]
	s_nop 0
	v_cvt_pk_bf16_f32 v76, v118, v119
	v_cvt_pk_bf16_f32 v77, v120, v121
	global_store_dwordx2 v[88:89], v[76:77], off offset:512 sc1
	v_pk_mul_f32 v[122:123], v[122:123], v[30:31] op_sel_hi:[1,0]
	v_pk_mul_f32 v[124:125], v[124:125], v[30:31] op_sel_hi:[1,0]
	v_pk_fma_f32 v[66:67], v[148:149], v[122:123], v[106:107]
	v_pk_fma_f32 v[68:69], v[150:151], v[124:125], v[108:109]
	global_store_dwordx4 v[86:87], v[66:69], off offset:2048 sc1 nt
	v_pk_fma_f32 v[122:123], v[234:235], v[66:67], v[218:219]
	v_pk_fma_f32 v[124:125], v[236:237], v[68:69], v[220:221]
	s_nop 0
	v_cvt_pk_bf16_f32 v78, v122, v123
	v_cvt_pk_bf16_f32 v79, v124, v125
	global_store_dwordx2 v[88:89], v[78:79], off offset:1024 sc1
	v_pk_mul_f32 v[126:127], v[126:127], v[30:31] op_sel_hi:[1,0]
	v_pk_mul_f32 v[128:129], v[128:129], v[30:31] op_sel_hi:[1,0]
	v_pk_fma_f32 v[70:71], v[152:153], v[126:127], v[110:111]
	v_pk_fma_f32 v[72:73], v[154:155], v[128:129], v[112:113]
	global_store_dwordx4 v[86:87], v[70:73], off offset:3072 sc1 nt
	v_pk_fma_f32 v[126:127], v[238:239], v[70:71], v[222:223]
	v_pk_fma_f32 v[128:129], v[240:241], v[72:73], v[224:225]
	s_nop 0
	v_cvt_pk_bf16_f32 v80, v126, v127
	v_cvt_pk_bf16_f32 v81, v128, v129
	global_store_dwordx2 v[88:89], v[80:81], off offset:1536 sc1
	v_lshl_add_u64 v[86:87], v[86:87], 0, s[0:1]
	v_lshl_add_u64 v[88:89], v[88:89], 0, s[20:21]
	s_branch .LBB0_53

.LBB0_124:
	s_bfe_u32 s0, s21, 0x20006
	s_ashr_i32 s6, s21, 6
	s_and_b32 s6, s6, -4
	s_xor_b32 s7, s0, 31
	s_sub_i32 s7, s7, s6
	s_and_b32 s1, s21, 0x100
	s_add_i32 s7, s7, 4
	s_or_b32 s0, s0, s6
	s_cmp_eq_u32 s1, 0
	v_writelane_b32 v255, s30, 2
	s_cselect_b32 s22, s0, s7
	s_and_b32 s23, s21, 3
	s_lshl_b32 s0, s23, 2
	v_readlane_b32 s1, v255, 24
	s_add_i32 s6, s0, s1
	s_add_i32 s0, s6, 1
	v_cvt_f32_i32_e32 v0, s0
	s_bfe_u32 s20, s21, 0x40002
	v_mov_b32_e32 v152, v194
	v_mul_f32_e32 v1, -0.5, v0
	v_cmp_gt_f32_e32 vcc, s82, v1
	s_and_b64 s[0:1], vcc, exec
	s_cselect_b32 s0, 0xffffffc0, 0
	v_cndmask_b32_e32 v1, 0, v182, vcc
	v_fmac_f32_e32 v1, -0.5, v0
	v_exp_f32_e32 v0, v1
	v_and_b32_e32 v153, 15, v152
	s_lshl_b32 s25, s22, 6
	s_lshl_b32 s30, s20, 11
	v_ldexp_f32 v82, v0, s0
	v_readlane_b32 s0, v255, 25
	v_mov_b64_e32 v[0:1], s[76:77]
	v_and_b32_e32 v32, 48, v152
	v_or_b32_e32 v85, s0, v153
	s_lshl_b32 s0, s6, 6
	s_mul_i32 s6, s6, 3
	v_or_b32_e32 v140, s25, v85
	s_ashr_i32 s7, s6, 31
	v_ashrrev_i32_e32 v141, 31, v140
	v_or_b32_e32 v88, 16, v85
	s_ashr_i32 s1, s0, 31
	s_lshl_b64 s[6:7], s[6:7], 1
	v_lshl_add_u64 v[130:131], v[140:141], 0, s[30:31]
	v_or_b32_e32 v142, s25, v88
	s_add_u32 s6, s6, 0x1400
	v_mad_u64_u32 v[2:3], s[18:19], v130, s83, v[0:1]
	v_ashrrev_i32_e32 v143, 31, v142
	s_addc_u32 s7, s7, 0
	v_mad_i32_i24 v3, v131, s83, v3
	s_lshl_b64 s[18:19], s[0:1], 1
	v_lshl_add_u64 v[132:133], v[142:143], 0, s[30:31]
	v_lshl_add_u64 v[4:5], v[2:3], 0, s[18:19]
	v_mad_u64_u32 v[0:1], s[0:1], v132, s83, v[0:1]
	v_lshl_add_u64 v[4:5], v[4:5], 0, v[32:33]
	v_lshl_add_u64 v[2:3], v[2:3], 0, s[6:7]
	v_writelane_b32 v255, s25, 29
	v_mad_i32_i24 v1, v133, s83, v1
	global_load_dwordx4 v[34:37], v[4:5], off
	global_load_dwordx4 v[38:41], v[4:5], off offset:64
	global_load_dword v156, v[2:3], off
	global_load_ushort v141, v[2:3], off offset:4
	v_writelane_b32 v255, s18, 17
	v_ashrrev_i32_e32 v155, 3, v152
	v_lshlrev_b32_e32 v50, 3, v152
	v_lshl_add_u64 v[2:3], v[0:1], 0, s[18:19]
	v_lshl_add_u64 v[2:3], v[2:3], 0, v[32:33]
	v_lshl_add_u64 v[0:1], v[0:1], 0, s[6:7]
	global_load_dwordx4 v[42:45], v[2:3], off
	global_load_dwordx4 v[46:49], v[2:3], off offset:64
	global_load_dword v157, v[0:1], off
	global_load_ushort v143, v[0:1], off offset:4
	s_mulk_i32 s20, 0x7f
	v_min_i32_e32 v0, 0x7e, v155
	v_writelane_b32 v255, s19, 18
	v_and_b32_e32 v84, 56, v50
	s_lshl_b32 s18, s23, 6
	v_add_u32_e32 v0, s20, v0
	v_or_b32_e32 v2, s18, v84
	v_ashrrev_i32_e32 v1, 31, v0
	v_lshlrev_b64 v[4:5], 9, v[0:1]
	v_lshlrev_b32_e32 v8, 1, v2
	v_readlane_b32 s6, v252, 13
	v_or_b32_e32 v4, v4, v8
	v_readlane_b32 s7, v252, 14
	s_barrier
	s_nop 0
	v_lshl_add_u64 v[0:1], s[6:7], 0, v[4:5]
	global_load_dwordx4 v[0:3], v[0:1], off
	v_readlane_b32 s34, v252, 15
	v_readlane_b32 s35, v252, 16
	s_movk_i32 s19, 0x48
	v_mad_u64_u32 v[6:7], s[0:1], v155, s19, v[84:85]
	v_lshl_add_u32 v196, v6, 1, 0
	v_add_u32_e32 v197, 0, v32
	v_lshl_add_u64 v[12:13], s[34:35], 0, v[4:5]
	global_load_dwordx4 v[12:15], v[12:13], off
	v_add_u32_e32 v16, 0x200, v152
	v_ashrrev_i32_e32 v6, 3, v16
	v_min_i32_e32 v16, 0x7e, v6
	v_add_u32_e32 v16, s20, v16
	v_ashrrev_i32_e32 v17, 31, v16
	v_lshlrev_b64 v[4:5], 9, v[16:17]
	v_or_b32_e32 v4, v4, v8
	v_lshl_add_u64 v[16:17], s[6:7], 0, v[4:5]
	global_load_dwordx4 v[16:19], v[16:17], off
	v_lshl_add_u64 v[20:21], s[34:35], 0, v[4:5]
	global_load_dwordx4 v[20:23], v[20:21], off
	v_mad_u64_u32 v[6:7], s[0:1], v6, s19, v[84:85]
	v_lshl_add_u32 v6, v6, 1, 0
	v_mad_u32_u24 v32, v153, s84, v197
	v_bfe_u32 v154, v152, 4, 2
	v_lshlrev_b32_e32 v195, 2, v154
	v_or_b32_e32 v83, 0x73, v195
	v_cmp_ne_u32_e64 s[40:41], 3, v154
	v_mov_b32_e32 v86, 0xf149f2ca
	v_mov_b32_e32 v51, 0xf149f2ca
	s_waitcnt vmcnt(3)
	ds_write_b128 v196, v[0:3] offset:36864
	s_waitcnt vmcnt(2)
	ds_write_b128 v196, v[12:15] offset:55296
	s_waitcnt vmcnt(1)
	ds_write_b128 v6, v[16:19] offset:36864
	s_waitcnt vmcnt(0)
	ds_write_b128 v6, v[20:23] offset:55296
	s_waitcnt lgkmcnt(0)
	s_barrier
	ds_read_b128 v[0:3], v32 offset:36864
	ds_read_b128 v[4:7], v32 offset:36928
	s_waitcnt lgkmcnt(1)
	v_mfma_f32_16x16x32_bf16 v[0:3], v[0:3], v[34:37], 0
	ds_read_b128 v[52:55], v32 offset:53056
	s_waitcnt lgkmcnt(1)
	v_mfma_f32_16x16x32_bf16 v[28:31], v[4:7], v[38:41], v[0:3]
	ds_read_b128 v[4:7], v32 offset:39232
	s_nop 3
	ds_read_b128 v[0:3], v32 offset:39168
	s_waitcnt lgkmcnt(0)
	v_mfma_f32_16x16x32_bf16 v[0:3], v[0:3], v[34:37], 0
	v_mfma_f32_16x16x32_bf16 v[24:27], v[4:7], v[38:41], v[0:3]
	ds_read_b128 v[4:7], v32 offset:41536
	s_nop 5
	ds_read_b128 v[0:3], v32 offset:41472
	s_waitcnt lgkmcnt(0)
	v_mfma_f32_16x16x32_bf16 v[0:3], v[0:3], v[34:37], 0
	v_mfma_f32_16x16x32_bf16 v[20:23], v[4:7], v[38:41], v[0:3]
	ds_read_b128 v[4:7], v32 offset:43840
	s_nop 5
	ds_read_b128 v[0:3], v32 offset:43776
	s_waitcnt lgkmcnt(0)
	v_mfma_f32_16x16x32_bf16 v[0:3], v[0:3], v[34:37], 0
	v_mfma_f32_16x16x32_bf16 v[16:19], v[4:7], v[38:41], v[0:3]
	ds_read_b128 v[4:7], v32 offset:46144
	s_nop 5
	ds_read_b128 v[0:3], v32 offset:46080
	s_waitcnt lgkmcnt(0)
	v_mfma_f32_16x16x32_bf16 v[0:3], v[0:3], v[34:37], 0
	v_mfma_f32_16x16x32_bf16 v[12:15], v[4:7], v[38:41], v[0:3]
	ds_read_b128 v[4:7], v32 offset:48448
	s_nop 5
	ds_read_b128 v[0:3], v32 offset:48384
	s_waitcnt lgkmcnt(0)
	v_mfma_f32_16x16x32_bf16 v[0:3], v[0:3], v[34:37], 0
	v_mfma_f32_16x16x32_bf16 v[8:11], v[4:7], v[38:41], v[0:3]
	ds_read_b128 v[4:7], v32 offset:50752
	s_nop 5
	ds_read_b128 v[0:3], v32 offset:50688
	s_waitcnt lgkmcnt(0)
	v_mfma_f32_16x16x32_bf16 v[0:3], v[0:3], v[34:37], 0
	v_mfma_f32_16x16x32_bf16 v[4:7], v[4:7], v[38:41], v[0:3]
	s_nop 6
	ds_read_b128 v[0:3], v32 offset:52992
	s_waitcnt lgkmcnt(0)
	v_mfma_f32_16x16x32_bf16 v[0:3], v[0:3], v[34:37], 0
	v_mfma_f32_16x16x32_bf16 v[0:3], v[52:55], v[38:41], v[0:3]
	s_and_saveexec_b64 s[6:7], s[40:41]
	s_cbranch_execz .LBB0_126
	v_lshl_add_u32 v32, v83, 4, 31
	v_sub_u32_e32 v51, v140, v32
	v_cvt_f32_i32_e32 v137, v51
	s_nop 2
	v_mov_b32_e32 v52, v3
	v_mov_b32_e32 v53, v82
	v_cmp_ge_i32_e32 vcc, v140, v32
	v_pk_mul_f32 v[52:53], v[52:53], v[136:137]
	s_nop 0
	v_sub_f32_e32 v3, v52, v53
	v_cndmask_b32_e32 v51, v183, v3, vcc
